# v54 + GEMM K-loop load segments: A-fragment LDS base precomputed once per step (v249), the two VALU address adds at each segment head removed (6.4 start-of-segment VALU)
# speedup vs baseline: 1.0090x; 1.0090x over previous
.LBB0_54:
	s_add_i32 m0, s28, 0x18000
	v_lshl_add_u64 v[0:1], v[0:1], 0, s[70:71]
	s_waitcnt vmcnt(2)
	s_barrier
	global_load_lds_dwordx4 v[0:1], off
	v_lshl_add_u64 v[0:1], v[2:3], 0, s[70:71]
	s_add_i32 m0, s28, 0x1a000
	s_add_i32 s81, s28, 0x8000
	global_load_lds_dwordx4 v[0:1], off
	v_lshl_add_u64 v[0:1], v[8:9], 0, s[70:71]
	s_mov_b32 m0, s81
	s_add_i32 s82, s28, 0xa000
	global_load_lds_dwordx4 v[0:1], off
	v_lshl_add_u64 v[0:1], v[10:11], 0, s[70:71]
	s_mov_b32 m0, s82
	v_bfe_u32 v20, v13, 4, 2
	global_load_lds_dwordx4 v[0:1], off
	s_add_i32 m0, s28, 0x1c000
	v_lshl_add_u64 v[0:1], v[4:5], 0, s[70:71]
	global_load_lds_dwordx4 v[0:1], off
	v_lshl_add_u64 v[0:1], v[6:7], 0, s[70:71]
	s_add_i32 m0, s28, 0x1e000
	v_and_b32_e32 v184, 15, v13
	global_load_lds_dwordx4 v[0:1], off
	v_rcp_iflag_f32_e32 v0, v12
	v_lshlrev_b32_e32 v22, 4, v20
	v_lshlrev_b32_e32 v23, 2, v13
	s_xor_b64 s[64:65], s[0:1], -1
	v_mul_f32_e32 v0, 0x4f7ffffe, v0
	v_cvt_u32_f32_e32 v0, v0
	s_and_b32 s77, s5, 3
	s_lshr_b32 s78, s3, 6
	v_lshl_or_b32 v22, v184, 6, v22
	s_lshl_b32 s0, s19, 13
	v_and_b32_e32 v23, 32, v23
	s_lshl_b32 s79, s19, 6
	v_bitop3_b32 v24, v22, s0, v23 bitop3:0xde
	s_lshl_b32 s0, s77, 12
	s_add_i32 s84, s78, -2
	s_cmpk_lt_u32 s2, 0x100
	v_bitop3_b32 v185, v22, s0, v23 bitop3:0xde
	v_add_u32_e32 v249, 0x10000, v185
	s_cselect_b64 s[66:67], -1, 0
	s_lshr_b32 s0, s24, 4
	v_readfirstlane_b32 s1, v0
	v_add_u32_e32 v0, v16, v14
	v_writelane_b32 v245, s0, 36
	s_sub_i32 s0, 0, s25
	v_add_lshl_u32 v0, v0, v15, 1
	v_mov_b32_e32 v1, v193
	s_waitcnt vmcnt(6)
	s_mul_i32 s0, s0, s1
	v_lshl_add_u64 v[162:163], s[30:31], 0, v[0:1]
	v_add_u32_e32 v0, v19, v17
	v_lshlrev_b32_e32 v21, 3, v20
	s_mul_hi_u32 s0, s1, s0
	v_add_lshl_u32 v0, v0, v18, 1
	v_lshl_or_b32 v186, s77, 5, v21
	v_and_b32_e32 v187, 63, v13
	s_mov_b32 s85, 0
	v_cmp_eq_u32_e64 s[36:37], 0, v20
	s_mov_b32 s19, s4
	s_add_i32 s2, s1, s0
	v_lshl_add_u64 v[164:165], s[30:31], 0, v[0:1]
	v_add_u32_e32 v188, 0, v24
	v_readfirstlane_b32 s33, v195
	s_nop 3
	s_lshr_b32 s33, s33, 6
	s_cmp_ge_u32 s33, 4
	s_cbranch_scc1 .Lmy_prio_done
	s_setprio 1

.LBB0_64:
	s_add_i32 s33, s42, 2
	s_add_u32 s46, s40, 0x80
	s_addc_u32 s43, s41, 0
	s_add_i32 s80, 0, 0x10000
	s_cmp_eq_u32 s84, s42
	s_cselect_b32 s43, s1, s43
	s_cselect_b32 s42, s0, s46
	s_cselect_b32 s47, s75, vcc_hi
	s_cselect_b32 s46, s74, vcc_lo
	s_add_i32 s5, 0, 0x14000
	ds_read_b128 v[128:131], v249
	ds_read_b128 v[132:135], v249 offset:1024
	ds_read_b128 v[136:139], v249 offset:2048
	ds_read_b128 v[140:143], v249 offset:3072
	ds_read_b128 v[144:147], v249 offset:16384
	ds_read_b128 v[148:151], v249 offset:17408
	ds_read_b128 v[152:155], v249 offset:18432
	ds_read_b128 v[166:169], v249 offset:19456
	v_lshl_add_u64 v[182:183], s[40:41], 0, v[162:163]
	s_add_i32 m0, s28, 0xc000
	ds_read_b128 v[170:173], v188
	ds_read_b128 v[174:177], v188 offset:1024
	ds_read_b128 v[178:181], v188 offset:2048
	ds_read_b128 v[214:217], v188 offset:3072
	ds_read_b128 v[218:221], v188 offset:4096
	ds_read_b128 v[222:225], v188 offset:5120
	ds_read_b128 v[226:229], v188 offset:6144
	ds_read_b128 v[230:233], v188 offset:7168
	global_load_lds_dwordx4 v[182:183], off
	v_lshl_add_u64 v[182:183], s[40:41], 0, v[164:165]
	s_add_i32 m0, s28, 0xe000
	s_nop 0
	global_load_lds_dwordx4 v[182:183], off
	s_waitcnt vmcnt(8)
	s_waitcnt lgkmcnt(0)
	s_barrier
	s_waitcnt lgkmcnt(0)
	v_mfma_f32_16x16x32_bf16 v[124:127], v[128:131], v[170:173], v[124:127]
	v_mfma_f32_16x16x32_bf16 v[120:123], v[136:139], v[170:173], v[120:123]
	v_mfma_f32_16x16x32_bf16 v[108:111], v[128:131], v[178:181], v[108:111]
	v_mfma_f32_16x16x32_bf16 v[104:107], v[136:139], v[178:181], v[104:107]
	v_mfma_f32_16x16x32_bf16 v[92:95], v[128:131], v[218:221], v[92:95]
	v_mfma_f32_16x16x32_bf16 v[88:91], v[136:139], v[218:221], v[88:91]
	v_mfma_f32_16x16x32_bf16 v[76:79], v[128:131], v[226:229], v[76:79]
	v_mfma_f32_16x16x32_bf16 v[72:75], v[136:139], v[226:229], v[72:75]
	v_mfma_f32_16x16x32_bf16 v[124:127], v[132:135], v[174:177], v[124:127]
	v_mfma_f32_16x16x32_bf16 v[120:123], v[140:143], v[174:177], v[120:123]
	v_mfma_f32_16x16x32_bf16 v[108:111], v[132:135], v[214:217], v[108:111]
	v_mfma_f32_16x16x32_bf16 v[104:107], v[140:143], v[214:217], v[104:107]
	v_mfma_f32_16x16x32_bf16 v[92:95], v[132:135], v[222:225], v[92:95]
	v_mfma_f32_16x16x32_bf16 v[88:91], v[140:143], v[222:225], v[88:91]
	v_mfma_f32_16x16x32_bf16 v[76:79], v[132:135], v[230:233], v[76:79]
	v_mfma_f32_16x16x32_bf16 v[72:75], v[140:143], v[230:233], v[72:75]
	v_mfma_f32_16x16x32_bf16 v[116:119], v[144:147], v[170:173], v[116:119]
	v_mfma_f32_16x16x32_bf16 v[112:115], v[152:155], v[170:173], v[112:115]
	v_mfma_f32_16x16x32_bf16 v[100:103], v[144:147], v[178:181], v[100:103]
	v_mfma_f32_16x16x32_bf16 v[96:99], v[152:155], v[178:181], v[96:99]
	v_mfma_f32_16x16x32_bf16 v[84:87], v[144:147], v[218:221], v[84:87]
	v_mfma_f32_16x16x32_bf16 v[80:83], v[152:155], v[218:221], v[80:83]
	v_mfma_f32_16x16x32_bf16 v[68:71], v[144:147], v[226:229], v[68:71]
	v_mfma_f32_16x16x32_bf16 v[64:67], v[152:155], v[226:229], v[64:67]
	v_mfma_f32_16x16x32_bf16 v[116:119], v[148:151], v[174:177], v[116:119]
	v_mfma_f32_16x16x32_bf16 v[112:115], v[166:169], v[174:177], v[112:115]
	v_mfma_f32_16x16x32_bf16 v[100:103], v[148:151], v[214:217], v[100:103]
	v_mfma_f32_16x16x32_bf16 v[96:99], v[166:169], v[214:217], v[96:99]
	v_mfma_f32_16x16x32_bf16 v[84:87], v[148:151], v[222:225], v[84:87]
	v_mfma_f32_16x16x32_bf16 v[80:83], v[166:169], v[222:225], v[80:83]
	v_mfma_f32_16x16x32_bf16 v[68:71], v[148:151], v[230:233], v[68:71]
	v_mfma_f32_16x16x32_bf16 v[64:67], v[166:169], v[230:233], v[64:67]
	s_barrier
	s_add_i32 s80, s80, s27
	v_lshl_add_u64 v[182:183], s[46:47], 0, v[192:193]
	s_mov_b32 m0, s80
	ds_read_b128 v[170:173], v188 offset:16384
	ds_read_b128 v[174:177], v188 offset:17408
	ds_read_b128 v[178:181], v188 offset:18432
	ds_read_b128 v[214:217], v188 offset:19456
	ds_read_b128 v[218:221], v188 offset:20480
	ds_read_b128 v[222:225], v188 offset:21504
	ds_read_b128 v[226:229], v188 offset:22528
	ds_read_b128 v[230:233], v188 offset:23552
	global_load_lds_dwordx4 v[182:183], off
	s_add_i32 m0, s80, 0x2000
	v_lshl_add_u64 v[190:191], s[46:47], 0, v[160:161]
	s_add_u32 s46, s46, s30
	s_addc_u32 s47, s47, 0
	s_add_i32 s5, s5, s27
	global_load_lds_dwordx4 v[190:191], off
	v_lshl_add_u64 v[200:201], s[46:47], 0, v[192:193]
	s_mov_b32 m0, s5
	v_lshl_add_u64 v[234:235], s[46:47], 0, v[160:161]
	global_load_lds_dwordx4 v[200:201], off
	s_add_i32 m0, s5, 0x2000
	v_lshl_add_u64 v[236:237], s[42:43], 0, v[156:157]
	global_load_lds_dwordx4 v[234:235], off
	s_mov_b32 m0, s28
	v_lshl_add_u64 v[238:239], s[42:43], 0, v[158:159]
	global_load_lds_dwordx4 v[236:237], off
	s_mov_b32 m0, s69
	s_nop 0
	global_load_lds_dwordx4 v[238:239], off
	s_waitcnt vmcnt(8)
	s_waitcnt lgkmcnt(0)
	s_barrier
	s_waitcnt lgkmcnt(0)
	v_mfma_f32_16x16x32_bf16 v[60:63], v[128:131], v[170:173], v[60:63]
	v_mfma_f32_16x16x32_bf16 v[56:59], v[136:139], v[170:173], v[56:59]
	v_mfma_f32_16x16x32_bf16 v[44:47], v[128:131], v[178:181], v[44:47]
	v_mfma_f32_16x16x32_bf16 v[40:43], v[136:139], v[178:181], v[40:43]
	v_mfma_f32_16x16x32_bf16 v[28:31], v[128:131], v[218:221], v[28:31]
	v_mfma_f32_16x16x32_bf16 v[24:27], v[136:139], v[218:221], v[24:27]
	v_mfma_f32_16x16x32_bf16 v[12:15], v[128:131], v[226:229], v[12:15]
	v_mfma_f32_16x16x32_bf16 v[8:11], v[136:139], v[226:229], v[8:11]
	v_mfma_f32_16x16x32_bf16 v[60:63], v[132:135], v[174:177], v[60:63]
	v_mfma_f32_16x16x32_bf16 v[56:59], v[140:143], v[174:177], v[56:59]
	v_mfma_f32_16x16x32_bf16 v[44:47], v[132:135], v[214:217], v[44:47]
	v_mfma_f32_16x16x32_bf16 v[40:43], v[140:143], v[214:217], v[40:43]
	v_mfma_f32_16x16x32_bf16 v[28:31], v[132:135], v[222:225], v[28:31]
	v_mfma_f32_16x16x32_bf16 v[24:27], v[140:143], v[222:225], v[24:27]
	v_mfma_f32_16x16x32_bf16 v[12:15], v[132:135], v[230:233], v[12:15]
	v_mfma_f32_16x16x32_bf16 v[8:11], v[140:143], v[230:233], v[8:11]
	v_mfma_f32_16x16x32_bf16 v[52:55], v[144:147], v[170:173], v[52:55]
	v_mfma_f32_16x16x32_bf16 v[48:51], v[152:155], v[170:173], v[48:51]
	v_mfma_f32_16x16x32_bf16 v[36:39], v[144:147], v[178:181], v[36:39]
	v_mfma_f32_16x16x32_bf16 v[32:35], v[152:155], v[178:181], v[32:35]
	v_mfma_f32_16x16x32_bf16 v[20:23], v[144:147], v[218:221], v[20:23]
	v_mfma_f32_16x16x32_bf16 v[16:19], v[152:155], v[218:221], v[16:19]
	v_mfma_f32_16x16x32_bf16 v[4:7], v[144:147], v[226:229], v[4:7]
	v_mfma_f32_16x16x32_bf16 v[0:3], v[152:155], v[226:229], v[0:3]
	v_mfma_f32_16x16x32_bf16 v[52:55], v[148:151], v[174:177], v[52:55]
	v_mfma_f32_16x16x32_bf16 v[48:51], v[166:169], v[174:177], v[48:51]
	v_mfma_f32_16x16x32_bf16 v[36:39], v[148:151], v[214:217], v[36:39]
	v_mfma_f32_16x16x32_bf16 v[32:35], v[166:169], v[214:217], v[32:35]
	v_mfma_f32_16x16x32_bf16 v[20:23], v[148:151], v[222:225], v[20:23]
	v_mfma_f32_16x16x32_bf16 v[16:19], v[166:169], v[222:225], v[16:19]
	v_mfma_f32_16x16x32_bf16 v[4:7], v[148:151], v[230:233], v[4:7]
	v_mfma_f32_16x16x32_bf16 v[0:3], v[166:169], v[230:233], v[0:3]
	s_barrier
.Lmy_sp3:
	s_add_i32 s5, 0, 0x18000
	s_add_i32 s46, 0, 0x1c000
	ds_read_b128 v[128:131], v249 offset:32768
	ds_read_b128 v[132:135], v249 offset:33792
	ds_read_b128 v[136:139], v249 offset:34816
	ds_read_b128 v[140:143], v249 offset:35840
	ds_read_b128 v[144:147], v249 offset:49152
	ds_read_b128 v[148:151], v249 offset:50176
	ds_read_b128 v[152:155], v249 offset:51200
	ds_read_b128 v[166:169], v249 offset:52224
	s_add_u32 s42, s42, s30
	s_addc_u32 s43, s43, 0
	s_mov_b32 m0, s72
	v_lshl_add_u64 v[240:241], s[42:43], 0, v[156:157]
	ds_read_b128 v[170:173], v188 offset:32768
	ds_read_b128 v[174:177], v188 offset:33792
	ds_read_b128 v[178:181], v188 offset:34816
	ds_read_b128 v[214:217], v188 offset:35840
	ds_read_b128 v[218:221], v188 offset:36864
	ds_read_b128 v[222:225], v188 offset:37888
	ds_read_b128 v[226:229], v188 offset:38912
	ds_read_b128 v[230:233], v188 offset:39936
	global_load_lds_dwordx4 v[240:241], off
	v_lshl_add_u64 v[240:241], s[42:43], 0, v[158:159]
	s_mov_b32 m0, s76
	s_nop 0
	global_load_lds_dwordx4 v[240:241], off
	s_waitcnt vmcnt(8)
	s_waitcnt lgkmcnt(0)
	s_barrier
	s_waitcnt lgkmcnt(0)
	v_mfma_f32_16x16x32_bf16 v[124:127], v[128:131], v[170:173], v[124:127]
	v_mfma_f32_16x16x32_bf16 v[120:123], v[136:139], v[170:173], v[120:123]
	v_mfma_f32_16x16x32_bf16 v[108:111], v[128:131], v[178:181], v[108:111]
	v_mfma_f32_16x16x32_bf16 v[104:107], v[136:139], v[178:181], v[104:107]
	v_mfma_f32_16x16x32_bf16 v[92:95], v[128:131], v[218:221], v[92:95]
	v_mfma_f32_16x16x32_bf16 v[88:91], v[136:139], v[218:221], v[88:91]
	v_mfma_f32_16x16x32_bf16 v[76:79], v[128:131], v[226:229], v[76:79]
	v_mfma_f32_16x16x32_bf16 v[72:75], v[136:139], v[226:229], v[72:75]
	v_mfma_f32_16x16x32_bf16 v[124:127], v[132:135], v[174:177], v[124:127]
	v_mfma_f32_16x16x32_bf16 v[120:123], v[140:143], v[174:177], v[120:123]
	v_mfma_f32_16x16x32_bf16 v[108:111], v[132:135], v[214:217], v[108:111]
	v_mfma_f32_16x16x32_bf16 v[104:107], v[140:143], v[214:217], v[104:107]
	v_mfma_f32_16x16x32_bf16 v[92:95], v[132:135], v[222:225], v[92:95]
	v_mfma_f32_16x16x32_bf16 v[88:91], v[140:143], v[222:225], v[88:91]
	v_mfma_f32_16x16x32_bf16 v[76:79], v[132:135], v[230:233], v[76:79]
	v_mfma_f32_16x16x32_bf16 v[72:75], v[140:143], v[230:233], v[72:75]
	v_mfma_f32_16x16x32_bf16 v[116:119], v[144:147], v[170:173], v[116:119]
	v_mfma_f32_16x16x32_bf16 v[112:115], v[152:155], v[170:173], v[112:115]
	v_mfma_f32_16x16x32_bf16 v[100:103], v[144:147], v[178:181], v[100:103]
	v_mfma_f32_16x16x32_bf16 v[96:99], v[152:155], v[178:181], v[96:99]
	v_mfma_f32_16x16x32_bf16 v[84:87], v[144:147], v[218:221], v[84:87]
	v_mfma_f32_16x16x32_bf16 v[80:83], v[152:155], v[218:221], v[80:83]
	v_mfma_f32_16x16x32_bf16 v[68:71], v[144:147], v[226:229], v[68:71]
	v_mfma_f32_16x16x32_bf16 v[64:67], v[152:155], v[226:229], v[64:67]
	v_mfma_f32_16x16x32_bf16 v[116:119], v[148:151], v[174:177], v[116:119]
	v_mfma_f32_16x16x32_bf16 v[112:115], v[166:169], v[174:177], v[112:115]
	v_mfma_f32_16x16x32_bf16 v[100:103], v[148:151], v[214:217], v[100:103]
	v_mfma_f32_16x16x32_bf16 v[96:99], v[166:169], v[214:217], v[96:99]
	v_mfma_f32_16x16x32_bf16 v[84:87], v[148:151], v[222:225], v[84:87]
	v_mfma_f32_16x16x32_bf16 v[80:83], v[166:169], v[222:225], v[80:83]
	v_mfma_f32_16x16x32_bf16 v[68:71], v[148:151], v[230:233], v[68:71]
	v_mfma_f32_16x16x32_bf16 v[64:67], v[166:169], v[230:233], v[64:67]
	s_barrier
	s_add_i32 s5, s5, s27
	v_lshl_add_u64 v[182:183], v[182:183], 0, s[70:71]
	s_mov_b32 m0, s5
	ds_read_b128 v[170:173], v188 offset:49152
	ds_read_b128 v[174:177], v188 offset:50176
	ds_read_b128 v[178:181], v188 offset:51200
	ds_read_b128 v[214:217], v188 offset:52224
	ds_read_b128 v[218:221], v188 offset:53248
	ds_read_b128 v[222:225], v188 offset:54272
	ds_read_b128 v[226:229], v188 offset:55296
	ds_read_b128 v[230:233], v188 offset:56320
	global_load_lds_dwordx4 v[182:183], off
	v_lshl_add_u64 v[182:183], v[190:191], 0, s[70:71]
	s_add_i32 m0, s5, 0x2000
	s_add_i32 s5, s46, s27
	global_load_lds_dwordx4 v[182:183], off
	v_lshl_add_u64 v[182:183], v[200:201], 0, s[70:71]
	s_mov_b32 m0, s5
	s_nop 0
	global_load_lds_dwordx4 v[182:183], off
	v_lshl_add_u64 v[182:183], v[234:235], 0, s[70:71]
	s_add_i32 m0, s5, 0x2000
	s_nop 0
	global_load_lds_dwordx4 v[182:183], off
	v_lshl_add_u64 v[182:183], v[236:237], 0, s[70:71]
	s_mov_b32 m0, s81
	s_nop 0
	global_load_lds_dwordx4 v[182:183], off
	v_lshl_add_u64 v[182:183], v[238:239], 0, s[70:71]
	s_mov_b32 m0, s82
	s_nop 0
	global_load_lds_dwordx4 v[182:183], off
	s_waitcnt vmcnt(8)
	s_waitcnt lgkmcnt(0)
	s_barrier
	s_waitcnt lgkmcnt(0)
	v_mfma_f32_16x16x32_bf16 v[60:63], v[128:131], v[170:173], v[60:63]
	v_mfma_f32_16x16x32_bf16 v[56:59], v[136:139], v[170:173], v[56:59]
	v_mfma_f32_16x16x32_bf16 v[44:47], v[128:131], v[178:181], v[44:47]
	v_mfma_f32_16x16x32_bf16 v[40:43], v[136:139], v[178:181], v[40:43]
	v_mfma_f32_16x16x32_bf16 v[28:31], v[128:131], v[218:221], v[28:31]
	v_mfma_f32_16x16x32_bf16 v[24:27], v[136:139], v[218:221], v[24:27]
	v_mfma_f32_16x16x32_bf16 v[12:15], v[128:131], v[226:229], v[12:15]
	v_mfma_f32_16x16x32_bf16 v[8:11], v[136:139], v[226:229], v[8:11]
	v_mfma_f32_16x16x32_bf16 v[60:63], v[132:135], v[174:177], v[60:63]
	v_mfma_f32_16x16x32_bf16 v[56:59], v[140:143], v[174:177], v[56:59]
	v_mfma_f32_16x16x32_bf16 v[44:47], v[132:135], v[214:217], v[44:47]
	v_mfma_f32_16x16x32_bf16 v[40:43], v[140:143], v[214:217], v[40:43]
	v_mfma_f32_16x16x32_bf16 v[28:31], v[132:135], v[222:225], v[28:31]
	v_mfma_f32_16x16x32_bf16 v[24:27], v[140:143], v[222:225], v[24:27]
	v_mfma_f32_16x16x32_bf16 v[12:15], v[132:135], v[230:233], v[12:15]
	v_mfma_f32_16x16x32_bf16 v[8:11], v[140:143], v[230:233], v[8:11]
	v_mfma_f32_16x16x32_bf16 v[52:55], v[144:147], v[170:173], v[52:55]
	v_mfma_f32_16x16x32_bf16 v[48:51], v[152:155], v[170:173], v[48:51]
	v_mfma_f32_16x16x32_bf16 v[36:39], v[144:147], v[178:181], v[36:39]
	v_mfma_f32_16x16x32_bf16 v[32:35], v[152:155], v[178:181], v[32:35]
	v_mfma_f32_16x16x32_bf16 v[20:23], v[144:147], v[218:221], v[20:23]
	v_mfma_f32_16x16x32_bf16 v[16:19], v[152:155], v[218:221], v[16:19]
	v_mfma_f32_16x16x32_bf16 v[4:7], v[144:147], v[226:229], v[4:7]
	v_mfma_f32_16x16x32_bf16 v[0:3], v[152:155], v[226:229], v[0:3]
	v_mfma_f32_16x16x32_bf16 v[52:55], v[148:151], v[174:177], v[52:55]
	v_mfma_f32_16x16x32_bf16 v[48:51], v[166:169], v[174:177], v[48:51]
	v_mfma_f32_16x16x32_bf16 v[36:39], v[148:151], v[214:217], v[36:39]
	v_mfma_f32_16x16x32_bf16 v[32:35], v[166:169], v[214:217], v[32:35]
	v_mfma_f32_16x16x32_bf16 v[20:23], v[148:151], v[222:225], v[20:23]
	v_mfma_f32_16x16x32_bf16 v[16:19], v[166:169], v[222:225], v[16:19]
	v_mfma_f32_16x16x32_bf16 v[4:7], v[148:151], v[230:233], v[4:7]
	v_mfma_f32_16x16x32_bf16 v[0:3], v[166:169], v[230:233], v[0:3]
	s_barrier
	s_add_u32 s40, s40, 0x100
	s_addc_u32 s41, s41, 0
	s_add_u32 vcc_lo, vcc_lo, 0x100
	s_addc_u32 vcc_hi, vcc_hi, 0
	s_cmp_ge_u32 s33, s78
	s_mov_b32 s42, s33
	s_cbranch_scc0 .LBB0_64
	s_and_b64 vcc, exec, s[66:67]
	s_cbranch_vccz .LBB0_67
	s_barrier

.Lmy_peel:
	s_add_i32 s33, s42, 2
	s_add_u32 s46, s40, 0x80
	s_addc_u32 s43, s41, 0
	s_add_i32 s80, 0, 0x10000
	s_cmp_eq_u32 s84, s42
	s_cselect_b32 s43, s1, s43
	s_cselect_b32 s42, s0, s46
	s_cselect_b32 s47, s75, vcc_hi
	s_cselect_b32 s46, s74, vcc_lo
	s_add_i32 s5, 0, 0x14000
	ds_read_b128 v[128:131], v249
	ds_read_b128 v[132:135], v249 offset:1024
	ds_read_b128 v[136:139], v249 offset:2048
	ds_read_b128 v[140:143], v249 offset:3072
	ds_read_b128 v[144:147], v249 offset:16384
	ds_read_b128 v[148:151], v249 offset:17408
	ds_read_b128 v[152:155], v249 offset:18432
	ds_read_b128 v[166:169], v249 offset:19456
	v_lshl_add_u64 v[182:183], s[40:41], 0, v[162:163]
	s_add_i32 m0, s28, 0xc000
	ds_read_b128 v[170:173], v188
	ds_read_b128 v[174:177], v188 offset:1024
	ds_read_b128 v[178:181], v188 offset:2048
	ds_read_b128 v[214:217], v188 offset:3072
	ds_read_b128 v[218:221], v188 offset:4096
	ds_read_b128 v[222:225], v188 offset:5120
	ds_read_b128 v[226:229], v188 offset:6144
	ds_read_b128 v[230:233], v188 offset:7168
	global_load_lds_dwordx4 v[182:183], off
	v_lshl_add_u64 v[182:183], s[40:41], 0, v[164:165]
	s_add_i32 m0, s28, 0xe000
	s_nop 0
	global_load_lds_dwordx4 v[182:183], off
	s_waitcnt vmcnt(24)
	s_waitcnt lgkmcnt(0)
	s_barrier
	s_waitcnt lgkmcnt(0)
	v_mfma_f32_16x16x32_bf16 v[124:127], v[128:131], v[170:173], 0
	v_mfma_f32_16x16x32_bf16 v[120:123], v[136:139], v[170:173], 0
	v_mfma_f32_16x16x32_bf16 v[108:111], v[128:131], v[178:181], 0
	v_mfma_f32_16x16x32_bf16 v[104:107], v[136:139], v[178:181], 0
	v_mfma_f32_16x16x32_bf16 v[92:95], v[128:131], v[218:221], 0
	v_mfma_f32_16x16x32_bf16 v[88:91], v[136:139], v[218:221], 0
	v_mfma_f32_16x16x32_bf16 v[76:79], v[128:131], v[226:229], 0
	v_mfma_f32_16x16x32_bf16 v[72:75], v[136:139], v[226:229], 0
	v_mfma_f32_16x16x32_bf16 v[124:127], v[132:135], v[174:177], v[124:127]
	v_mfma_f32_16x16x32_bf16 v[120:123], v[140:143], v[174:177], v[120:123]
	v_mfma_f32_16x16x32_bf16 v[108:111], v[132:135], v[214:217], v[108:111]
	v_mfma_f32_16x16x32_bf16 v[104:107], v[140:143], v[214:217], v[104:107]
	v_mfma_f32_16x16x32_bf16 v[92:95], v[132:135], v[222:225], v[92:95]
	v_mfma_f32_16x16x32_bf16 v[88:91], v[140:143], v[222:225], v[88:91]
	v_mfma_f32_16x16x32_bf16 v[76:79], v[132:135], v[230:233], v[76:79]
	v_mfma_f32_16x16x32_bf16 v[72:75], v[140:143], v[230:233], v[72:75]
	v_mfma_f32_16x16x32_bf16 v[116:119], v[144:147], v[170:173], 0
	v_mfma_f32_16x16x32_bf16 v[112:115], v[152:155], v[170:173], 0
	v_mfma_f32_16x16x32_bf16 v[100:103], v[144:147], v[178:181], 0
	v_mfma_f32_16x16x32_bf16 v[96:99], v[152:155], v[178:181], 0
	v_mfma_f32_16x16x32_bf16 v[84:87], v[144:147], v[218:221], 0
	v_mfma_f32_16x16x32_bf16 v[80:83], v[152:155], v[218:221], 0
	v_mfma_f32_16x16x32_bf16 v[68:71], v[144:147], v[226:229], 0
	v_mfma_f32_16x16x32_bf16 v[64:67], v[152:155], v[226:229], 0
	v_mfma_f32_16x16x32_bf16 v[116:119], v[148:151], v[174:177], v[116:119]
	v_mfma_f32_16x16x32_bf16 v[112:115], v[166:169], v[174:177], v[112:115]
	v_mfma_f32_16x16x32_bf16 v[100:103], v[148:151], v[214:217], v[100:103]
	v_mfma_f32_16x16x32_bf16 v[96:99], v[166:169], v[214:217], v[96:99]
	v_mfma_f32_16x16x32_bf16 v[84:87], v[148:151], v[222:225], v[84:87]
	v_mfma_f32_16x16x32_bf16 v[80:83], v[166:169], v[222:225], v[80:83]
	v_mfma_f32_16x16x32_bf16 v[68:71], v[148:151], v[230:233], v[68:71]
	v_mfma_f32_16x16x32_bf16 v[64:67], v[166:169], v[230:233], v[64:67]
	s_barrier
	s_add_i32 s80, s80, s27
	v_lshl_add_u64 v[182:183], s[46:47], 0, v[192:193]
	s_mov_b32 m0, s80
	ds_read_b128 v[170:173], v188 offset:16384
	ds_read_b128 v[174:177], v188 offset:17408
	ds_read_b128 v[178:181], v188 offset:18432
	ds_read_b128 v[214:217], v188 offset:19456
	ds_read_b128 v[218:221], v188 offset:20480
	ds_read_b128 v[222:225], v188 offset:21504
	ds_read_b128 v[226:229], v188 offset:22528
	ds_read_b128 v[230:233], v188 offset:23552
	global_load_lds_dwordx4 v[182:183], off
	s_add_i32 m0, s80, 0x2000
	v_lshl_add_u64 v[190:191], s[46:47], 0, v[160:161]
	s_add_u32 s46, s46, s30
	s_addc_u32 s47, s47, 0
	s_add_i32 s5, s5, s27
	global_load_lds_dwordx4 v[190:191], off
	v_lshl_add_u64 v[200:201], s[46:47], 0, v[192:193]
	s_mov_b32 m0, s5
	v_lshl_add_u64 v[234:235], s[46:47], 0, v[160:161]
	global_load_lds_dwordx4 v[200:201], off
	s_add_i32 m0, s5, 0x2000
	v_lshl_add_u64 v[236:237], s[42:43], 0, v[156:157]
	global_load_lds_dwordx4 v[234:235], off
	s_mov_b32 m0, s28
	v_lshl_add_u64 v[238:239], s[42:43], 0, v[158:159]
	global_load_lds_dwordx4 v[236:237], off
	s_mov_b32 m0, s69
	s_nop 0
	global_load_lds_dwordx4 v[238:239], off
	s_waitcnt vmcnt(24)
	s_waitcnt lgkmcnt(0)
	s_barrier
	s_waitcnt lgkmcnt(0)
	v_mfma_f32_16x16x32_bf16 v[60:63], v[128:131], v[170:173], 0
	v_mfma_f32_16x16x32_bf16 v[56:59], v[136:139], v[170:173], 0
	v_mfma_f32_16x16x32_bf16 v[44:47], v[128:131], v[178:181], 0
	v_mfma_f32_16x16x32_bf16 v[40:43], v[136:139], v[178:181], 0
	v_mfma_f32_16x16x32_bf16 v[28:31], v[128:131], v[218:221], 0
	v_mfma_f32_16x16x32_bf16 v[24:27], v[136:139], v[218:221], 0
	v_mfma_f32_16x16x32_bf16 v[12:15], v[128:131], v[226:229], 0
	v_mfma_f32_16x16x32_bf16 v[8:11], v[136:139], v[226:229], 0
	v_mfma_f32_16x16x32_bf16 v[60:63], v[132:135], v[174:177], v[60:63]
	v_mfma_f32_16x16x32_bf16 v[56:59], v[140:143], v[174:177], v[56:59]
	v_mfma_f32_16x16x32_bf16 v[44:47], v[132:135], v[214:217], v[44:47]
	v_mfma_f32_16x16x32_bf16 v[40:43], v[140:143], v[214:217], v[40:43]
	v_mfma_f32_16x16x32_bf16 v[28:31], v[132:135], v[222:225], v[28:31]
	v_mfma_f32_16x16x32_bf16 v[24:27], v[140:143], v[222:225], v[24:27]
	v_mfma_f32_16x16x32_bf16 v[12:15], v[132:135], v[230:233], v[12:15]
	v_mfma_f32_16x16x32_bf16 v[8:11], v[140:143], v[230:233], v[8:11]
	v_mfma_f32_16x16x32_bf16 v[52:55], v[144:147], v[170:173], 0
	v_mfma_f32_16x16x32_bf16 v[48:51], v[152:155], v[170:173], 0
	v_mfma_f32_16x16x32_bf16 v[36:39], v[144:147], v[178:181], 0
	v_mfma_f32_16x16x32_bf16 v[32:35], v[152:155], v[178:181], 0
	v_mfma_f32_16x16x32_bf16 v[20:23], v[144:147], v[218:221], 0
	v_mfma_f32_16x16x32_bf16 v[16:19], v[152:155], v[218:221], 0
	v_mfma_f32_16x16x32_bf16 v[4:7], v[144:147], v[226:229], 0
	v_mfma_f32_16x16x32_bf16 v[0:3], v[152:155], v[226:229], 0
	v_mfma_f32_16x16x32_bf16 v[52:55], v[148:151], v[174:177], v[52:55]
	v_mfma_f32_16x16x32_bf16 v[48:51], v[166:169], v[174:177], v[48:51]
	v_mfma_f32_16x16x32_bf16 v[36:39], v[148:151], v[214:217], v[36:39]
	v_mfma_f32_16x16x32_bf16 v[32:35], v[166:169], v[214:217], v[32:35]
	v_mfma_f32_16x16x32_bf16 v[20:23], v[148:151], v[222:225], v[20:23]
	v_mfma_f32_16x16x32_bf16 v[16:19], v[166:169], v[222:225], v[16:19]
	v_mfma_f32_16x16x32_bf16 v[4:7], v[148:151], v[230:233], v[4:7]
	v_mfma_f32_16x16x32_bf16 v[0:3], v[166:169], v[230:233], v[0:3]
	s_barrier
	s_branch .Lmy_sp3
